# v41 with MFMA order: second operand (A-fragment) constant for 4 consecutive MFMAs
# baseline (speedup 1.0000x reference)
.LBB0_159:
	s_add_u32 s0, s22, 0xfff80080
	s_addc_u32 s1, s23, -1
	s_add_i32 s51, 0, 0x10000
	s_cmp_eq_u32 s50, 28
	s_cselect_b32 s27, s15, s1
	s_cselect_b32 s26, s46, s0
	v_add_u32_e32 v140, s51, v143
	s_cselect_b32 s25, s13, s49
	s_cselect_b32 s24, s47, s48
	s_add_i32 s0, 0, 0x14000
	ds_read_b128 v[146:149], v140
	ds_read_b128 v[150:153], v140 offset:1024
	ds_read_b128 v[154:157], v140 offset:2048
	ds_read_b128 v[158:161], v140 offset:3072
	v_add_u32_e32 v140, s0, v143
	ds_read_b128 v[162:165], v140
	ds_read_b128 v[166:169], v140 offset:1024
	ds_read_b128 v[170:173], v140 offset:2048
	ds_read_b128 v[174:177], v140 offset:3072
	v_lshl_add_u64 v[140:141], s[22:23], 0, v[136:137]
	s_add_i32 m0, s35, 0xc000
	ds_read_b128 v[178:181], v144
	ds_read_b128 v[182:185], v144 offset:1024
	ds_read_b128 v[192:195], v144 offset:2048
	ds_read_b128 v[196:199], v144 offset:3072
	ds_read_b128 v[200:203], v144 offset:4096
	ds_read_b128 v[204:207], v144 offset:5120
	ds_read_b128 v[208:211], v144 offset:6144
	ds_read_b128 v[212:215], v144 offset:7168
	global_load_lds_dwordx4 v[140:141], off
	v_lshl_add_u64 v[140:141], s[22:23], 0, v[138:139]
	s_add_i32 m0, s35, 0xe000
	s_nop 0
	global_load_lds_dwordx4 v[140:141], off
	s_waitcnt vmcnt(8)
	s_waitcnt lgkmcnt(0)
	s_setprio 1
	s_barrier

	v_mfma_f32_16x16x32_bf16 v[126:129], v[146:149], v[178:181], v[126:129]
	v_mfma_f32_16x16x32_bf16 v[118:121], v[154:157], v[178:181], v[118:121]
	v_mfma_f32_16x16x32_bf16 v[122:125], v[162:165], v[178:181], v[122:125]
	v_mfma_f32_16x16x32_bf16 v[114:117], v[170:173], v[178:181], v[114:117]
	v_mfma_f32_16x16x32_bf16 v[110:113], v[146:149], v[192:195], v[110:113]
	v_mfma_f32_16x16x32_bf16 v[102:105], v[154:157], v[192:195], v[102:105]
	v_mfma_f32_16x16x32_bf16 v[106:109], v[162:165], v[192:195], v[106:109]
	v_mfma_f32_16x16x32_bf16 v[98:101], v[170:173], v[192:195], v[98:101]
	v_mfma_f32_16x16x32_bf16 v[94:97], v[146:149], v[200:203], v[94:97]
	v_mfma_f32_16x16x32_bf16 v[86:89], v[154:157], v[200:203], v[86:89]
	v_mfma_f32_16x16x32_bf16 v[90:93], v[162:165], v[200:203], v[90:93]
	v_mfma_f32_16x16x32_bf16 v[82:85], v[170:173], v[200:203], v[82:85]
	v_mfma_f32_16x16x32_bf16 v[78:81], v[146:149], v[208:211], v[78:81]
	v_mfma_f32_16x16x32_bf16 v[70:73], v[154:157], v[208:211], v[70:73]
	v_mfma_f32_16x16x32_bf16 v[74:77], v[162:165], v[208:211], v[74:77]
	v_mfma_f32_16x16x32_bf16 v[66:69], v[170:173], v[208:211], v[66:69]


	v_mfma_f32_16x16x32_bf16 v[126:129], v[150:153], v[182:185], v[126:129]
	v_mfma_f32_16x16x32_bf16 v[118:121], v[158:161], v[182:185], v[118:121]
	v_mfma_f32_16x16x32_bf16 v[122:125], v[166:169], v[182:185], v[122:125]
	v_mfma_f32_16x16x32_bf16 v[114:117], v[174:177], v[182:185], v[114:117]
	v_mfma_f32_16x16x32_bf16 v[110:113], v[150:153], v[196:199], v[110:113]
	v_mfma_f32_16x16x32_bf16 v[102:105], v[158:161], v[196:199], v[102:105]
	v_mfma_f32_16x16x32_bf16 v[106:109], v[166:169], v[196:199], v[106:109]
	v_mfma_f32_16x16x32_bf16 v[98:101], v[174:177], v[196:199], v[98:101]
	v_mfma_f32_16x16x32_bf16 v[94:97], v[150:153], v[204:207], v[94:97]
	v_mfma_f32_16x16x32_bf16 v[86:89], v[158:161], v[204:207], v[86:89]
	v_mfma_f32_16x16x32_bf16 v[90:93], v[166:169], v[204:207], v[90:93]
	v_mfma_f32_16x16x32_bf16 v[82:85], v[174:177], v[204:207], v[82:85]
	v_mfma_f32_16x16x32_bf16 v[78:81], v[150:153], v[212:215], v[78:81]
	v_mfma_f32_16x16x32_bf16 v[70:73], v[158:161], v[212:215], v[70:73]
	v_mfma_f32_16x16x32_bf16 v[74:77], v[166:169], v[212:215], v[74:77]
	v_mfma_f32_16x16x32_bf16 v[66:69], v[174:177], v[212:215], v[66:69]
	s_barrier
	s_setprio 0
	s_add_i32 s1, s51, s31
	v_lshl_add_u64 v[140:141], s[24:25], 0, v[186:187]
	s_mov_b32 m0, s1
	ds_read_b128 v[178:181], v144 offset:16384
	ds_read_b128 v[182:185], v144 offset:17408
	ds_read_b128 v[192:195], v144 offset:18432
	ds_read_b128 v[196:199], v144 offset:19456
	ds_read_b128 v[200:203], v144 offset:20480
	ds_read_b128 v[204:207], v144 offset:21504
	ds_read_b128 v[208:211], v144 offset:22528
	ds_read_b128 v[212:215], v144 offset:23552
	global_load_lds_dwordx4 v[140:141], off
	s_add_i32 m0, s1, 0x2000
	s_add_u32 s52, s24, 0x80000
	v_lshl_add_u64 v[216:217], s[24:25], 0, v[130:131]
	s_addc_u32 s53, s25, 0
	s_add_i32 s0, s0, s31
	global_load_lds_dwordx4 v[216:217], off
	v_lshl_add_u64 v[218:219], s[52:53], 0, v[186:187]
	s_mov_b32 m0, s0
	v_lshl_add_u64 v[220:221], s[26:27], 0, v[132:133]
	global_load_lds_dwordx4 v[218:219], off
	v_lshl_add_u64 v[218:219], s[52:53], 0, v[130:131]
	s_add_i32 m0, s0, 0x2000
	s_nop 0
	global_load_lds_dwordx4 v[218:219], off
	v_lshl_add_u64 v[218:219], s[26:27], 0, v[134:135]
	s_mov_b32 m0, s35
	s_nop 0
	global_load_lds_dwordx4 v[218:219], off
	s_mov_b32 m0, s36
	s_nop 0
	global_load_lds_dwordx4 v[220:221], off
	s_waitcnt vmcnt(8)
	s_waitcnt lgkmcnt(0)
	s_setprio 1
	s_barrier

	v_mfma_f32_16x16x32_bf16 v[62:65], v[146:149], v[178:181], v[62:65]
	v_mfma_f32_16x16x32_bf16 v[54:57], v[154:157], v[178:181], v[54:57]
	v_mfma_f32_16x16x32_bf16 v[58:61], v[162:165], v[178:181], v[58:61]
	v_mfma_f32_16x16x32_bf16 v[50:53], v[170:173], v[178:181], v[50:53]
	v_mfma_f32_16x16x32_bf16 v[46:49], v[146:149], v[192:195], v[46:49]
	v_mfma_f32_16x16x32_bf16 v[38:41], v[154:157], v[192:195], v[38:41]
	v_mfma_f32_16x16x32_bf16 v[42:45], v[162:165], v[192:195], v[42:45]
	v_mfma_f32_16x16x32_bf16 v[34:37], v[170:173], v[192:195], v[34:37]
	v_mfma_f32_16x16x32_bf16 v[30:33], v[146:149], v[200:203], v[30:33]
	v_mfma_f32_16x16x32_bf16 v[22:25], v[154:157], v[200:203], v[22:25]
	v_mfma_f32_16x16x32_bf16 v[26:29], v[162:165], v[200:203], v[26:29]
	v_mfma_f32_16x16x32_bf16 v[18:21], v[170:173], v[200:203], v[18:21]
	v_mfma_f32_16x16x32_bf16 v[14:17], v[146:149], v[208:211], v[14:17]
	v_mfma_f32_16x16x32_bf16 v[6:9], v[154:157], v[208:211], v[6:9]
	v_mfma_f32_16x16x32_bf16 v[10:13], v[162:165], v[208:211], v[10:13]
	v_mfma_f32_16x16x32_bf16 v[2:5], v[170:173], v[208:211], v[2:5]


	v_mfma_f32_16x16x32_bf16 v[62:65], v[150:153], v[182:185], v[62:65]
	v_mfma_f32_16x16x32_bf16 v[54:57], v[158:161], v[182:185], v[54:57]
	v_mfma_f32_16x16x32_bf16 v[58:61], v[166:169], v[182:185], v[58:61]
	v_mfma_f32_16x16x32_bf16 v[50:53], v[174:177], v[182:185], v[50:53]
	v_mfma_f32_16x16x32_bf16 v[46:49], v[150:153], v[196:199], v[46:49]
	v_mfma_f32_16x16x32_bf16 v[38:41], v[158:161], v[196:199], v[38:41]
	v_mfma_f32_16x16x32_bf16 v[42:45], v[166:169], v[196:199], v[42:45]
	v_mfma_f32_16x16x32_bf16 v[34:37], v[174:177], v[196:199], v[34:37]
	v_mfma_f32_16x16x32_bf16 v[30:33], v[150:153], v[204:207], v[30:33]
	v_mfma_f32_16x16x32_bf16 v[22:25], v[158:161], v[204:207], v[22:25]
	v_mfma_f32_16x16x32_bf16 v[26:29], v[166:169], v[204:207], v[26:29]
	v_mfma_f32_16x16x32_bf16 v[18:21], v[174:177], v[204:207], v[18:21]
	v_mfma_f32_16x16x32_bf16 v[14:17], v[150:153], v[212:215], v[14:17]
	v_mfma_f32_16x16x32_bf16 v[6:9], v[158:161], v[212:215], v[6:9]
	v_mfma_f32_16x16x32_bf16 v[10:13], v[166:169], v[212:215], v[10:13]
	v_mfma_f32_16x16x32_bf16 v[2:5], v[174:177], v[212:215], v[2:5]
	s_barrier
	s_setprio 0
	s_add_i32 s0, 0, 0x18000
	v_add_u32_e32 v145, s0, v143
	s_add_i32 s1, 0, 0x1c000
	ds_read_b128 v[146:149], v145
	ds_read_b128 v[150:153], v145 offset:1024
	ds_read_b128 v[154:157], v145 offset:2048
	ds_read_b128 v[158:161], v145 offset:3072
	v_add_u32_e32 v145, s1, v143
	ds_read_b128 v[162:165], v145
	ds_read_b128 v[166:169], v145 offset:1024
	ds_read_b128 v[170:173], v145 offset:2048
	ds_read_b128 v[174:177], v145 offset:3072
	s_add_u32 s26, s26, 0x80000
	s_addc_u32 s27, s27, 0
	s_mov_b32 m0, s37
	v_lshl_add_u64 v[222:223], s[26:27], 0, v[134:135]
	ds_read_b128 v[178:181], v144 offset:32768
	ds_read_b128 v[182:185], v144 offset:33792
	ds_read_b128 v[192:195], v144 offset:34816
	ds_read_b128 v[196:199], v144 offset:35840
	ds_read_b128 v[200:203], v144 offset:36864
	ds_read_b128 v[204:207], v144 offset:37888
	ds_read_b128 v[208:211], v144 offset:38912
	ds_read_b128 v[212:215], v144 offset:39936
	global_load_lds_dwordx4 v[222:223], off
	v_lshl_add_u64 v[222:223], s[26:27], 0, v[132:133]
	s_mov_b32 m0, s38
	s_nop 0
	global_load_lds_dwordx4 v[222:223], off
	s_waitcnt vmcnt(8)
	s_waitcnt lgkmcnt(0)
	s_setprio 1
	s_barrier

	v_mfma_f32_16x16x32_bf16 v[126:129], v[146:149], v[178:181], v[126:129]
	v_mfma_f32_16x16x32_bf16 v[118:121], v[154:157], v[178:181], v[118:121]
	v_mfma_f32_16x16x32_bf16 v[122:125], v[162:165], v[178:181], v[122:125]
	v_mfma_f32_16x16x32_bf16 v[114:117], v[170:173], v[178:181], v[114:117]
	v_mfma_f32_16x16x32_bf16 v[110:113], v[146:149], v[192:195], v[110:113]
	v_mfma_f32_16x16x32_bf16 v[102:105], v[154:157], v[192:195], v[102:105]
	v_mfma_f32_16x16x32_bf16 v[106:109], v[162:165], v[192:195], v[106:109]
	v_mfma_f32_16x16x32_bf16 v[98:101], v[170:173], v[192:195], v[98:101]
	v_mfma_f32_16x16x32_bf16 v[94:97], v[146:149], v[200:203], v[94:97]
	v_mfma_f32_16x16x32_bf16 v[86:89], v[154:157], v[200:203], v[86:89]
	v_mfma_f32_16x16x32_bf16 v[90:93], v[162:165], v[200:203], v[90:93]
	v_mfma_f32_16x16x32_bf16 v[82:85], v[170:173], v[200:203], v[82:85]
	v_mfma_f32_16x16x32_bf16 v[78:81], v[146:149], v[208:211], v[78:81]
	v_mfma_f32_16x16x32_bf16 v[70:73], v[154:157], v[208:211], v[70:73]
	v_mfma_f32_16x16x32_bf16 v[74:77], v[162:165], v[208:211], v[74:77]
	v_mfma_f32_16x16x32_bf16 v[66:69], v[170:173], v[208:211], v[66:69]


	v_mfma_f32_16x16x32_bf16 v[126:129], v[150:153], v[182:185], v[126:129]
	v_mfma_f32_16x16x32_bf16 v[118:121], v[158:161], v[182:185], v[118:121]
	v_mfma_f32_16x16x32_bf16 v[122:125], v[166:169], v[182:185], v[122:125]
	v_mfma_f32_16x16x32_bf16 v[114:117], v[174:177], v[182:185], v[114:117]
	v_mfma_f32_16x16x32_bf16 v[110:113], v[150:153], v[196:199], v[110:113]
	v_mfma_f32_16x16x32_bf16 v[102:105], v[158:161], v[196:199], v[102:105]
	v_mfma_f32_16x16x32_bf16 v[106:109], v[166:169], v[196:199], v[106:109]
	v_mfma_f32_16x16x32_bf16 v[98:101], v[174:177], v[196:199], v[98:101]
	v_mfma_f32_16x16x32_bf16 v[94:97], v[150:153], v[204:207], v[94:97]
	v_mfma_f32_16x16x32_bf16 v[86:89], v[158:161], v[204:207], v[86:89]
	v_mfma_f32_16x16x32_bf16 v[90:93], v[166:169], v[204:207], v[90:93]
	v_mfma_f32_16x16x32_bf16 v[82:85], v[174:177], v[204:207], v[82:85]
	v_mfma_f32_16x16x32_bf16 v[78:81], v[150:153], v[212:215], v[78:81]
	v_mfma_f32_16x16x32_bf16 v[70:73], v[158:161], v[212:215], v[70:73]
	v_mfma_f32_16x16x32_bf16 v[74:77], v[166:169], v[212:215], v[74:77]
	v_mfma_f32_16x16x32_bf16 v[66:69], v[174:177], v[212:215], v[66:69]
	s_barrier
	s_setprio 0
	s_add_i32 s0, s0, s31
	v_lshl_add_u64 v[140:141], v[140:141], 0, s[84:85]
	s_mov_b32 m0, s0
	ds_read_b128 v[178:181], v144 offset:49152
	ds_read_b128 v[182:185], v144 offset:50176
	ds_read_b128 v[192:195], v144 offset:51200
	ds_read_b128 v[196:199], v144 offset:52224
	ds_read_b128 v[200:203], v144 offset:53248
	ds_read_b128 v[204:207], v144 offset:54272
	ds_read_b128 v[208:211], v144 offset:55296
	ds_read_b128 v[212:215], v144 offset:56320
	global_load_lds_dwordx4 v[140:141], off
	s_add_i32 m0, s0, 0x2000
	s_add_u32 s24, s24, 0x80080
	v_lshl_add_u64 v[140:141], v[216:217], 0, s[84:85]
	s_addc_u32 s25, s25, 0
	s_add_i32 s0, s1, s31
	global_load_lds_dwordx4 v[140:141], off
	v_lshl_add_u64 v[140:141], s[24:25], 0, v[186:187]
	s_mov_b32 m0, s0
	s_nop 0
	global_load_lds_dwordx4 v[140:141], off
	v_lshl_add_u64 v[140:141], s[24:25], 0, v[130:131]
	s_add_i32 m0, s0, 0x2000
	s_nop 0
	global_load_lds_dwordx4 v[140:141], off
	v_lshl_add_u64 v[140:141], v[218:219], 0, s[84:85]
	s_mov_b32 m0, s39
	s_nop 0
	global_load_lds_dwordx4 v[140:141], off
	v_lshl_add_u64 v[140:141], v[220:221], 0, s[84:85]
	s_mov_b32 m0, s40
	s_nop 0
	global_load_lds_dwordx4 v[140:141], off
	s_waitcnt vmcnt(8)
	s_waitcnt lgkmcnt(0)
	s_setprio 1
	s_barrier

	v_mfma_f32_16x16x32_bf16 v[62:65], v[146:149], v[178:181], v[62:65]
	v_mfma_f32_16x16x32_bf16 v[54:57], v[154:157], v[178:181], v[54:57]
	v_mfma_f32_16x16x32_bf16 v[58:61], v[162:165], v[178:181], v[58:61]
	v_mfma_f32_16x16x32_bf16 v[50:53], v[170:173], v[178:181], v[50:53]
	v_mfma_f32_16x16x32_bf16 v[46:49], v[146:149], v[192:195], v[46:49]
	v_mfma_f32_16x16x32_bf16 v[38:41], v[154:157], v[192:195], v[38:41]
	v_mfma_f32_16x16x32_bf16 v[42:45], v[162:165], v[192:195], v[42:45]
	v_mfma_f32_16x16x32_bf16 v[34:37], v[170:173], v[192:195], v[34:37]
	v_mfma_f32_16x16x32_bf16 v[30:33], v[146:149], v[200:203], v[30:33]
	v_mfma_f32_16x16x32_bf16 v[22:25], v[154:157], v[200:203], v[22:25]
	v_mfma_f32_16x16x32_bf16 v[26:29], v[162:165], v[200:203], v[26:29]
	v_mfma_f32_16x16x32_bf16 v[18:21], v[170:173], v[200:203], v[18:21]
	v_mfma_f32_16x16x32_bf16 v[14:17], v[146:149], v[208:211], v[14:17]
	v_mfma_f32_16x16x32_bf16 v[6:9], v[154:157], v[208:211], v[6:9]
	v_mfma_f32_16x16x32_bf16 v[10:13], v[162:165], v[208:211], v[10:13]
	v_mfma_f32_16x16x32_bf16 v[2:5], v[170:173], v[208:211], v[2:5]


	v_mfma_f32_16x16x32_bf16 v[62:65], v[150:153], v[182:185], v[62:65]
	v_mfma_f32_16x16x32_bf16 v[54:57], v[158:161], v[182:185], v[54:57]
	v_mfma_f32_16x16x32_bf16 v[58:61], v[166:169], v[182:185], v[58:61]
	v_mfma_f32_16x16x32_bf16 v[50:53], v[174:177], v[182:185], v[50:53]
	v_mfma_f32_16x16x32_bf16 v[46:49], v[150:153], v[196:199], v[46:49]
	v_mfma_f32_16x16x32_bf16 v[38:41], v[158:161], v[196:199], v[38:41]
	v_mfma_f32_16x16x32_bf16 v[42:45], v[166:169], v[196:199], v[42:45]
	v_mfma_f32_16x16x32_bf16 v[34:37], v[174:177], v[196:199], v[34:37]
	v_mfma_f32_16x16x32_bf16 v[30:33], v[150:153], v[204:207], v[30:33]
	v_mfma_f32_16x16x32_bf16 v[22:25], v[158:161], v[204:207], v[22:25]
	v_mfma_f32_16x16x32_bf16 v[26:29], v[166:169], v[204:207], v[26:29]
	v_mfma_f32_16x16x32_bf16 v[18:21], v[174:177], v[204:207], v[18:21]
	v_mfma_f32_16x16x32_bf16 v[14:17], v[150:153], v[212:215], v[14:17]
	v_mfma_f32_16x16x32_bf16 v[6:9], v[158:161], v[212:215], v[6:9]
	v_mfma_f32_16x16x32_bf16 v[10:13], v[166:169], v[212:215], v[10:13]
	v_mfma_f32_16x16x32_bf16 v[2:5], v[174:177], v[212:215], v[2:5]
	s_barrier
	s_setprio 0
	s_add_i32 s50, s50, 2
	s_add_u32 s22, s22, 0x100
	s_addc_u32 s23, s23, 0
	s_add_u32 s48, s48, 0x100
	s_addc_u32 s49, s49, 0
	s_cmp_gt_u32 s50, 29
	s_cbranch_scc0 .LBB0_159
	s_and_b64 vcc, exec, s[10:11]
	s_cbranch_vccz .LBB0_162
	s_barrier

.LBB0_243:
	s_add_u32 s22, s20, 0x100
	s_addc_u32 s23, s21, 0
	s_add_i32 s0, 0, 0x10000
	s_cmpk_eq_i32 s51, 0x54
	s_cselect_b32 s27, s7, s23
	s_cselect_b32 s26, s6, s22
	s_cselect_b32 s25, s19, s50
	s_cselect_b32 s24, s18, s49
	s_add_i32 s1, 0, 0x14000
	v_add_u32_e32 v126, s0, v237
	v_add_u32_e32 v158, s1, v237
	ds_read_b128 v[90:93], v126
	ds_read_b128 v[102:105], v126 offset:1024
	ds_read_b128 v[114:117], v126 offset:2048
	ds_read_b128 v[126:129], v126 offset:3072
	ds_read_b128 v[138:141], v158
	ds_read_b128 v[142:145], v158 offset:1024
	ds_read_b128 v[154:157], v158 offset:2048
	ds_read_b128 v[158:161], v158 offset:3072
	v_lshl_add_u64 v[210:211], s[20:21], 0, v[198:199]
	s_add_i32 m0, s34, 0xc000
	ds_read_b128 v[162:165], v238
	ds_read_b128 v[166:169], v238 offset:1024
	ds_read_b128 v[170:173], v238 offset:2048
	ds_read_b128 v[174:177], v238 offset:3072
	ds_read_b128 v[178:181], v238 offset:4096
	ds_read_b128 v[182:185], v238 offset:5120
	ds_read_b128 v[202:205], v238 offset:6144
	ds_read_b128 v[206:209], v238 offset:7168
	global_load_lds_dwordx4 v[210:211], off
	v_lshl_add_u64 v[210:211], s[20:21], 0, v[200:201]
	s_add_i32 m0, s34, 0xe000
	s_nop 0
	global_load_lds_dwordx4 v[210:211], off
	s_waitcnt vmcnt(8)
	s_waitcnt lgkmcnt(0)
	s_setprio 1
	s_barrier

	v_mfma_f32_16x16x32_bf16 v[150:153], v[90:93], v[162:165], v[150:153]
	v_mfma_f32_16x16x32_bf16 v[146:149], v[114:117], v[162:165], v[146:149]
	v_mfma_f32_16x16x32_bf16 v[134:137], v[138:141], v[162:165], v[134:137]
	v_mfma_f32_16x16x32_bf16 v[130:133], v[154:157], v[162:165], v[130:133]
	v_mfma_f32_16x16x32_bf16 v[122:125], v[90:93], v[170:173], v[122:125]
	v_mfma_f32_16x16x32_bf16 v[118:121], v[114:117], v[170:173], v[118:121]
	v_mfma_f32_16x16x32_bf16 v[110:113], v[138:141], v[170:173], v[110:113]
	v_mfma_f32_16x16x32_bf16 v[106:109], v[154:157], v[170:173], v[106:109]
	v_mfma_f32_16x16x32_bf16 v[98:101], v[90:93], v[178:181], v[98:101]
	v_mfma_f32_16x16x32_bf16 v[94:97], v[114:117], v[178:181], v[94:97]
	v_mfma_f32_16x16x32_bf16 v[86:89], v[138:141], v[178:181], v[86:89]
	v_mfma_f32_16x16x32_bf16 v[82:85], v[154:157], v[178:181], v[82:85]
	v_mfma_f32_16x16x32_bf16 v[78:81], v[90:93], v[202:205], v[78:81]
	v_mfma_f32_16x16x32_bf16 v[74:77], v[114:117], v[202:205], v[74:77]
	v_mfma_f32_16x16x32_bf16 v[70:73], v[138:141], v[202:205], v[70:73]
	v_mfma_f32_16x16x32_bf16 v[66:69], v[154:157], v[202:205], v[66:69]


	v_mfma_f32_16x16x32_bf16 v[150:153], v[102:105], v[166:169], v[150:153]
	v_mfma_f32_16x16x32_bf16 v[146:149], v[126:129], v[166:169], v[146:149]
	v_mfma_f32_16x16x32_bf16 v[134:137], v[142:145], v[166:169], v[134:137]
	v_mfma_f32_16x16x32_bf16 v[130:133], v[158:161], v[166:169], v[130:133]
	v_mfma_f32_16x16x32_bf16 v[122:125], v[102:105], v[174:177], v[122:125]
	v_mfma_f32_16x16x32_bf16 v[118:121], v[126:129], v[174:177], v[118:121]
	v_mfma_f32_16x16x32_bf16 v[110:113], v[142:145], v[174:177], v[110:113]
	v_mfma_f32_16x16x32_bf16 v[106:109], v[158:161], v[174:177], v[106:109]
	v_mfma_f32_16x16x32_bf16 v[98:101], v[102:105], v[182:185], v[98:101]
	v_mfma_f32_16x16x32_bf16 v[94:97], v[126:129], v[182:185], v[94:97]
	v_mfma_f32_16x16x32_bf16 v[86:89], v[142:145], v[182:185], v[86:89]
	v_mfma_f32_16x16x32_bf16 v[82:85], v[158:161], v[182:185], v[82:85]
	v_mfma_f32_16x16x32_bf16 v[78:81], v[102:105], v[206:209], v[78:81]
	v_mfma_f32_16x16x32_bf16 v[74:77], v[126:129], v[206:209], v[74:77]
	v_mfma_f32_16x16x32_bf16 v[70:73], v[142:145], v[206:209], v[70:73]
	v_mfma_f32_16x16x32_bf16 v[66:69], v[158:161], v[206:209], v[66:69]
	s_barrier
	s_setprio 0
	s_add_i32 s0, s0, s31
	v_lshl_add_u64 v[210:211], s[24:25], 0, v[186:187]
	s_mov_b32 m0, s0
	ds_read_b128 v[162:165], v238 offset:16384
	ds_read_b128 v[166:169], v238 offset:17408
	ds_read_b128 v[170:173], v238 offset:18432
	ds_read_b128 v[174:177], v238 offset:19456
	ds_read_b128 v[178:181], v238 offset:20480
	ds_read_b128 v[182:185], v238 offset:21504
	ds_read_b128 v[202:205], v238 offset:22528
	ds_read_b128 v[206:209], v238 offset:23552
	global_load_lds_dwordx4 v[210:211], off
	s_add_i32 m0, s0, 0x2000
	s_add_u32 s20, s24, 0x160000
	v_lshl_add_u64 v[212:213], s[24:25], 0, v[196:197]
	s_addc_u32 s21, s25, 0
	s_add_i32 s0, s1, s31
	global_load_lds_dwordx4 v[212:213], off
	v_lshl_add_u64 v[214:215], s[20:21], 0, v[186:187]
	s_mov_b32 m0, s0
	v_lshl_add_u64 v[216:217], s[26:27], 0, v[194:195]
	global_load_lds_dwordx4 v[214:215], off
	v_lshl_add_u64 v[214:215], s[20:21], 0, v[196:197]
	s_add_i32 m0, s0, 0x2000
	s_nop 0
	global_load_lds_dwordx4 v[214:215], off
	v_lshl_add_u64 v[214:215], s[26:27], 0, v[192:193]
	s_mov_b32 m0, s34
	s_nop 0
	global_load_lds_dwordx4 v[214:215], off
	s_mov_b32 m0, s35
	s_nop 0
	global_load_lds_dwordx4 v[216:217], off
	s_waitcnt vmcnt(8)
	s_waitcnt lgkmcnt(0)
	s_setprio 1
	s_barrier

	v_mfma_f32_16x16x32_bf16 v[62:65], v[90:93], v[162:165], v[62:65]
	v_mfma_f32_16x16x32_bf16 v[58:61], v[114:117], v[162:165], v[58:61]
	v_mfma_f32_16x16x32_bf16 v[54:57], v[138:141], v[162:165], v[54:57]
	v_mfma_f32_16x16x32_bf16 v[50:53], v[154:157], v[162:165], v[50:53]
	v_mfma_f32_16x16x32_bf16 v[46:49], v[90:93], v[170:173], v[46:49]
	v_mfma_f32_16x16x32_bf16 v[42:45], v[114:117], v[170:173], v[42:45]
	v_mfma_f32_16x16x32_bf16 v[38:41], v[138:141], v[170:173], v[38:41]
	v_mfma_f32_16x16x32_bf16 v[34:37], v[154:157], v[170:173], v[34:37]
	v_mfma_f32_16x16x32_bf16 v[30:33], v[90:93], v[178:181], v[30:33]
	v_mfma_f32_16x16x32_bf16 v[26:29], v[114:117], v[178:181], v[26:29]
	v_mfma_f32_16x16x32_bf16 v[22:25], v[138:141], v[178:181], v[22:25]
	v_mfma_f32_16x16x32_bf16 v[18:21], v[154:157], v[178:181], v[18:21]
	v_mfma_f32_16x16x32_bf16 v[14:17], v[90:93], v[202:205], v[14:17]
	v_mfma_f32_16x16x32_bf16 v[10:13], v[114:117], v[202:205], v[10:13]
	v_mfma_f32_16x16x32_bf16 v[6:9], v[138:141], v[202:205], v[6:9]
	v_mfma_f32_16x16x32_bf16 v[2:5], v[154:157], v[202:205], v[2:5]


	v_mfma_f32_16x16x32_bf16 v[62:65], v[102:105], v[166:169], v[62:65]
	v_mfma_f32_16x16x32_bf16 v[58:61], v[126:129], v[166:169], v[58:61]
	v_mfma_f32_16x16x32_bf16 v[54:57], v[142:145], v[166:169], v[54:57]
	v_mfma_f32_16x16x32_bf16 v[50:53], v[158:161], v[166:169], v[50:53]
	v_mfma_f32_16x16x32_bf16 v[46:49], v[102:105], v[174:177], v[46:49]
	v_mfma_f32_16x16x32_bf16 v[42:45], v[126:129], v[174:177], v[42:45]
	v_mfma_f32_16x16x32_bf16 v[38:41], v[142:145], v[174:177], v[38:41]
	v_mfma_f32_16x16x32_bf16 v[34:37], v[158:161], v[174:177], v[34:37]
	v_mfma_f32_16x16x32_bf16 v[30:33], v[102:105], v[182:185], v[30:33]
	v_mfma_f32_16x16x32_bf16 v[26:29], v[126:129], v[182:185], v[26:29]
	v_mfma_f32_16x16x32_bf16 v[22:25], v[142:145], v[182:185], v[22:25]
	v_mfma_f32_16x16x32_bf16 v[18:21], v[158:161], v[182:185], v[18:21]
	v_mfma_f32_16x16x32_bf16 v[14:17], v[102:105], v[206:209], v[14:17]
	v_mfma_f32_16x16x32_bf16 v[10:13], v[126:129], v[206:209], v[10:13]
	v_mfma_f32_16x16x32_bf16 v[6:9], v[142:145], v[206:209], v[6:9]
	v_mfma_f32_16x16x32_bf16 v[2:5], v[158:161], v[206:209], v[2:5]
	s_barrier
	s_setprio 0
	s_add_i32 s0, 0, 0x18000
	s_add_i32 s1, 0, 0x1c000
	v_add_u32_e32 v126, s0, v237
	v_add_u32_e32 v158, s1, v237
	ds_read_b128 v[90:93], v126
	ds_read_b128 v[102:105], v126 offset:1024
	ds_read_b128 v[114:117], v126 offset:2048
	ds_read_b128 v[126:129], v126 offset:3072
	ds_read_b128 v[138:141], v158
	ds_read_b128 v[142:145], v158 offset:1024
	ds_read_b128 v[154:157], v158 offset:2048
	ds_read_b128 v[158:161], v158 offset:3072
	s_add_u32 s20, s26, 0x160000
	s_addc_u32 s21, s27, 0
	s_mov_b32 m0, s36
	v_lshl_add_u64 v[218:219], s[20:21], 0, v[192:193]
	ds_read_b128 v[162:165], v238 offset:32768
	ds_read_b128 v[166:169], v238 offset:33792
	ds_read_b128 v[170:173], v238 offset:34816
	ds_read_b128 v[174:177], v238 offset:35840
	ds_read_b128 v[178:181], v238 offset:36864
	ds_read_b128 v[182:185], v238 offset:37888
	ds_read_b128 v[202:205], v238 offset:38912
	ds_read_b128 v[206:209], v238 offset:39936
	global_load_lds_dwordx4 v[218:219], off
	v_lshl_add_u64 v[218:219], s[20:21], 0, v[194:195]
	s_mov_b32 m0, s37
	s_nop 0
	global_load_lds_dwordx4 v[218:219], off
	s_waitcnt vmcnt(8)
	s_waitcnt lgkmcnt(0)
	s_setprio 1
	s_barrier

	v_mfma_f32_16x16x32_bf16 v[150:153], v[90:93], v[162:165], v[150:153]
	v_mfma_f32_16x16x32_bf16 v[146:149], v[114:117], v[162:165], v[146:149]
	v_mfma_f32_16x16x32_bf16 v[134:137], v[138:141], v[162:165], v[134:137]
	v_mfma_f32_16x16x32_bf16 v[130:133], v[154:157], v[162:165], v[130:133]
	v_mfma_f32_16x16x32_bf16 v[122:125], v[90:93], v[170:173], v[122:125]
	v_mfma_f32_16x16x32_bf16 v[118:121], v[114:117], v[170:173], v[118:121]
	v_mfma_f32_16x16x32_bf16 v[110:113], v[138:141], v[170:173], v[110:113]
	v_mfma_f32_16x16x32_bf16 v[106:109], v[154:157], v[170:173], v[106:109]
	v_mfma_f32_16x16x32_bf16 v[98:101], v[90:93], v[178:181], v[98:101]
	v_mfma_f32_16x16x32_bf16 v[94:97], v[114:117], v[178:181], v[94:97]
	v_mfma_f32_16x16x32_bf16 v[86:89], v[138:141], v[178:181], v[86:89]
	v_mfma_f32_16x16x32_bf16 v[82:85], v[154:157], v[178:181], v[82:85]
	v_mfma_f32_16x16x32_bf16 v[78:81], v[90:93], v[202:205], v[78:81]
	v_mfma_f32_16x16x32_bf16 v[74:77], v[114:117], v[202:205], v[74:77]
	v_mfma_f32_16x16x32_bf16 v[70:73], v[138:141], v[202:205], v[70:73]
	v_mfma_f32_16x16x32_bf16 v[66:69], v[154:157], v[202:205], v[66:69]


	v_mfma_f32_16x16x32_bf16 v[150:153], v[102:105], v[166:169], v[150:153]
	v_mfma_f32_16x16x32_bf16 v[146:149], v[126:129], v[166:169], v[146:149]
	v_mfma_f32_16x16x32_bf16 v[134:137], v[142:145], v[166:169], v[134:137]
	v_mfma_f32_16x16x32_bf16 v[130:133], v[158:161], v[166:169], v[130:133]
	v_mfma_f32_16x16x32_bf16 v[122:125], v[102:105], v[174:177], v[122:125]
	v_mfma_f32_16x16x32_bf16 v[118:121], v[126:129], v[174:177], v[118:121]
	v_mfma_f32_16x16x32_bf16 v[110:113], v[142:145], v[174:177], v[110:113]
	v_mfma_f32_16x16x32_bf16 v[106:109], v[158:161], v[174:177], v[106:109]
	v_mfma_f32_16x16x32_bf16 v[98:101], v[102:105], v[182:185], v[98:101]
	v_mfma_f32_16x16x32_bf16 v[94:97], v[126:129], v[182:185], v[94:97]
	v_mfma_f32_16x16x32_bf16 v[86:89], v[142:145], v[182:185], v[86:89]
	v_mfma_f32_16x16x32_bf16 v[82:85], v[158:161], v[182:185], v[82:85]
	v_mfma_f32_16x16x32_bf16 v[78:81], v[102:105], v[206:209], v[78:81]
	v_mfma_f32_16x16x32_bf16 v[74:77], v[126:129], v[206:209], v[74:77]
	v_mfma_f32_16x16x32_bf16 v[70:73], v[142:145], v[206:209], v[70:73]
	v_mfma_f32_16x16x32_bf16 v[66:69], v[158:161], v[206:209], v[66:69]
	s_barrier
	s_setprio 0
	s_add_i32 s0, s0, s31
	v_lshl_add_u64 v[210:211], v[210:211], 0, s[84:85]
	s_mov_b32 m0, s0
	ds_read_b128 v[162:165], v238 offset:49152
	ds_read_b128 v[166:169], v238 offset:50176
	ds_read_b128 v[170:173], v238 offset:51200
	ds_read_b128 v[174:177], v238 offset:52224
	ds_read_b128 v[178:181], v238 offset:53248
	ds_read_b128 v[182:185], v238 offset:54272
	ds_read_b128 v[202:205], v238 offset:55296
	ds_read_b128 v[206:209], v238 offset:56320
	global_load_lds_dwordx4 v[210:211], off
	s_add_i32 m0, s0, 0x2000
	s_add_u32 s20, s24, 0x160080
	v_lshl_add_u64 v[210:211], v[212:213], 0, s[84:85]
	s_addc_u32 s21, s25, 0
	s_add_i32 s0, s1, s31
	global_load_lds_dwordx4 v[210:211], off
	v_lshl_add_u64 v[210:211], s[20:21], 0, v[186:187]
	s_mov_b32 m0, s0
	s_nop 0
	global_load_lds_dwordx4 v[210:211], off
	v_lshl_add_u64 v[210:211], s[20:21], 0, v[196:197]
	s_add_i32 m0, s0, 0x2000
	s_nop 0
	global_load_lds_dwordx4 v[210:211], off
	v_lshl_add_u64 v[210:211], v[214:215], 0, s[84:85]
	s_mov_b32 m0, s41
	s_nop 0
	global_load_lds_dwordx4 v[210:211], off
	v_lshl_add_u64 v[210:211], v[216:217], 0, s[84:85]
	s_mov_b32 m0, s42
	s_nop 0
	global_load_lds_dwordx4 v[210:211], off
	s_waitcnt vmcnt(8)
	s_waitcnt lgkmcnt(0)
	s_setprio 1
	s_barrier

	v_mfma_f32_16x16x32_bf16 v[62:65], v[90:93], v[162:165], v[62:65]
	v_mfma_f32_16x16x32_bf16 v[58:61], v[114:117], v[162:165], v[58:61]
	v_mfma_f32_16x16x32_bf16 v[54:57], v[138:141], v[162:165], v[54:57]
	v_mfma_f32_16x16x32_bf16 v[50:53], v[154:157], v[162:165], v[50:53]
	v_mfma_f32_16x16x32_bf16 v[46:49], v[90:93], v[170:173], v[46:49]
	v_mfma_f32_16x16x32_bf16 v[42:45], v[114:117], v[170:173], v[42:45]
	v_mfma_f32_16x16x32_bf16 v[38:41], v[138:141], v[170:173], v[38:41]
	v_mfma_f32_16x16x32_bf16 v[34:37], v[154:157], v[170:173], v[34:37]
	v_mfma_f32_16x16x32_bf16 v[30:33], v[90:93], v[178:181], v[30:33]
	v_mfma_f32_16x16x32_bf16 v[26:29], v[114:117], v[178:181], v[26:29]
	v_mfma_f32_16x16x32_bf16 v[22:25], v[138:141], v[178:181], v[22:25]
	v_mfma_f32_16x16x32_bf16 v[18:21], v[154:157], v[178:181], v[18:21]
	v_mfma_f32_16x16x32_bf16 v[14:17], v[90:93], v[202:205], v[14:17]
	v_mfma_f32_16x16x32_bf16 v[10:13], v[114:117], v[202:205], v[10:13]
	v_mfma_f32_16x16x32_bf16 v[6:9], v[138:141], v[202:205], v[6:9]
	v_mfma_f32_16x16x32_bf16 v[2:5], v[154:157], v[202:205], v[2:5]


	v_mfma_f32_16x16x32_bf16 v[62:65], v[102:105], v[166:169], v[62:65]
	v_mfma_f32_16x16x32_bf16 v[58:61], v[126:129], v[166:169], v[58:61]
	v_mfma_f32_16x16x32_bf16 v[54:57], v[142:145], v[166:169], v[54:57]
	v_mfma_f32_16x16x32_bf16 v[50:53], v[158:161], v[166:169], v[50:53]
	v_mfma_f32_16x16x32_bf16 v[46:49], v[102:105], v[174:177], v[46:49]
	v_mfma_f32_16x16x32_bf16 v[42:45], v[126:129], v[174:177], v[42:45]
	v_mfma_f32_16x16x32_bf16 v[38:41], v[142:145], v[174:177], v[38:41]
	v_mfma_f32_16x16x32_bf16 v[34:37], v[158:161], v[174:177], v[34:37]
	v_mfma_f32_16x16x32_bf16 v[30:33], v[102:105], v[182:185], v[30:33]
	v_mfma_f32_16x16x32_bf16 v[26:29], v[126:129], v[182:185], v[26:29]
	v_mfma_f32_16x16x32_bf16 v[22:25], v[142:145], v[182:185], v[22:25]
	v_mfma_f32_16x16x32_bf16 v[18:21], v[158:161], v[182:185], v[18:21]
	v_mfma_f32_16x16x32_bf16 v[14:17], v[102:105], v[206:209], v[14:17]
	v_mfma_f32_16x16x32_bf16 v[10:13], v[126:129], v[206:209], v[10:13]
	v_mfma_f32_16x16x32_bf16 v[6:9], v[142:145], v[206:209], v[6:9]
	v_mfma_f32_16x16x32_bf16 v[2:5], v[158:161], v[206:209], v[2:5]
	s_barrier
	s_setprio 0
	s_add_i32 s51, s51, 2
	s_add_u32 s49, s49, 0x100
	s_addc_u32 s50, s50, 0
	s_cmpk_gt_u32 s51, 0x55
	s_mov_b64 s[20:21], s[22:23]
	s_cbranch_scc0 .LBB0_243
	s_and_b64 vcc, exec, s[16:17]
	s_cbranch_vccz .LBB0_246
	s_barrier

.LBB0_443:
	s_add_u32 s0, s26, 0xfff80080
	s_addc_u32 s1, s27, -1
	s_add_i32 s56, 0, 0x10000
	s_cmp_eq_u32 s55, 28
	s_cselect_b32 s31, s19, s1
	s_cselect_b32 s30, s51, s0
	v_add_u32_e32 v140, s56, v144
	s_cselect_b32 s29, s17, s54
	s_cselect_b32 s28, s52, s53
	s_add_i32 s0, 0, 0x14000
	ds_read_b128 v[146:149], v140
	ds_read_b128 v[150:153], v140 offset:1024
	ds_read_b128 v[154:157], v140 offset:2048
	ds_read_b128 v[158:161], v140 offset:3072
	v_add_u32_e32 v140, s0, v144
	ds_read_b128 v[162:165], v140
	ds_read_b128 v[166:169], v140 offset:1024
	ds_read_b128 v[170:173], v140 offset:2048
	ds_read_b128 v[174:177], v140 offset:3072
	v_lshl_add_u64 v[140:141], s[26:27], 0, v[136:137]
	s_add_i32 m0, s25, 0xc000
	ds_read_b128 v[178:181], v145
	ds_read_b128 v[182:185], v145 offset:1024
	ds_read_b128 v[192:195], v145 offset:2048
	ds_read_b128 v[196:199], v145 offset:3072
	ds_read_b128 v[200:203], v145 offset:4096
	ds_read_b128 v[204:207], v145 offset:5120
	ds_read_b128 v[208:211], v145 offset:6144
	ds_read_b128 v[212:215], v145 offset:7168
	global_load_lds_dwordx4 v[140:141], off
	v_lshl_add_u64 v[140:141], s[26:27], 0, v[138:139]
	s_add_i32 m0, s25, 0xe000
	s_nop 0
	global_load_lds_dwordx4 v[140:141], off
	s_waitcnt vmcnt(8)
	s_waitcnt lgkmcnt(0)
	s_setprio 1
	s_barrier

	v_mfma_f32_16x16x32_bf16 v[126:129], v[146:149], v[178:181], v[126:129]
	v_mfma_f32_16x16x32_bf16 v[122:125], v[154:157], v[178:181], v[122:125]
	v_mfma_f32_16x16x32_bf16 v[118:121], v[162:165], v[178:181], v[118:121]
	v_mfma_f32_16x16x32_bf16 v[110:113], v[170:173], v[178:181], v[110:113]
	v_mfma_f32_16x16x32_bf16 v[114:117], v[146:149], v[192:195], v[114:117]
	v_mfma_f32_16x16x32_bf16 v[106:109], v[154:157], v[192:195], v[106:109]
	v_mfma_f32_16x16x32_bf16 v[102:105], v[162:165], v[192:195], v[102:105]
	v_mfma_f32_16x16x32_bf16 v[94:97], v[170:173], v[192:195], v[94:97]
	v_mfma_f32_16x16x32_bf16 v[98:101], v[146:149], v[200:203], v[98:101]
	v_mfma_f32_16x16x32_bf16 v[90:93], v[154:157], v[200:203], v[90:93]
	v_mfma_f32_16x16x32_bf16 v[86:89], v[162:165], v[200:203], v[86:89]
	v_mfma_f32_16x16x32_bf16 v[78:81], v[170:173], v[200:203], v[78:81]
	v_mfma_f32_16x16x32_bf16 v[82:85], v[146:149], v[208:211], v[82:85]
	v_mfma_f32_16x16x32_bf16 v[74:77], v[154:157], v[208:211], v[74:77]
	v_mfma_f32_16x16x32_bf16 v[70:73], v[162:165], v[208:211], v[70:73]
	v_mfma_f32_16x16x32_bf16 v[66:69], v[170:173], v[208:211], v[66:69]


	v_mfma_f32_16x16x32_bf16 v[126:129], v[150:153], v[182:185], v[126:129]
	v_mfma_f32_16x16x32_bf16 v[122:125], v[158:161], v[182:185], v[122:125]
	v_mfma_f32_16x16x32_bf16 v[118:121], v[166:169], v[182:185], v[118:121]
	v_mfma_f32_16x16x32_bf16 v[110:113], v[174:177], v[182:185], v[110:113]
	v_mfma_f32_16x16x32_bf16 v[114:117], v[150:153], v[196:199], v[114:117]
	v_mfma_f32_16x16x32_bf16 v[106:109], v[158:161], v[196:199], v[106:109]
	v_mfma_f32_16x16x32_bf16 v[102:105], v[166:169], v[196:199], v[102:105]
	v_mfma_f32_16x16x32_bf16 v[94:97], v[174:177], v[196:199], v[94:97]
	v_mfma_f32_16x16x32_bf16 v[98:101], v[150:153], v[204:207], v[98:101]
	v_mfma_f32_16x16x32_bf16 v[90:93], v[158:161], v[204:207], v[90:93]
	v_mfma_f32_16x16x32_bf16 v[86:89], v[166:169], v[204:207], v[86:89]
	v_mfma_f32_16x16x32_bf16 v[78:81], v[174:177], v[204:207], v[78:81]
	v_mfma_f32_16x16x32_bf16 v[82:85], v[150:153], v[212:215], v[82:85]
	v_mfma_f32_16x16x32_bf16 v[74:77], v[158:161], v[212:215], v[74:77]
	v_mfma_f32_16x16x32_bf16 v[70:73], v[166:169], v[212:215], v[70:73]
	v_mfma_f32_16x16x32_bf16 v[66:69], v[174:177], v[212:215], v[66:69]
	s_barrier
	s_setprio 0
	s_add_i32 s1, s56, s39
	v_lshl_add_u64 v[140:141], s[28:29], 0, v[186:187]
	s_mov_b32 m0, s1
	ds_read_b128 v[178:181], v145 offset:16384
	ds_read_b128 v[182:185], v145 offset:17408
	ds_read_b128 v[192:195], v145 offset:18432
	ds_read_b128 v[196:199], v145 offset:19456
	ds_read_b128 v[200:203], v145 offset:20480
	ds_read_b128 v[204:207], v145 offset:21504
	ds_read_b128 v[208:211], v145 offset:22528
	ds_read_b128 v[212:215], v145 offset:23552
	global_load_lds_dwordx4 v[140:141], off
	s_add_i32 m0, s1, 0x2000
	s_add_u32 s56, s28, 0x80000
	v_lshl_add_u64 v[188:189], s[28:29], 0, v[130:131]
	s_addc_u32 s57, s29, 0
	s_add_i32 s0, s0, s39
	global_load_lds_dwordx4 v[188:189], off
	v_lshl_add_u64 v[216:217], s[56:57], 0, v[186:187]
	s_mov_b32 m0, s0
	v_lshl_add_u64 v[218:219], s[30:31], 0, v[132:133]
	global_load_lds_dwordx4 v[216:217], off
	v_lshl_add_u64 v[216:217], s[56:57], 0, v[130:131]
	s_add_i32 m0, s0, 0x2000
	s_nop 0
	global_load_lds_dwordx4 v[216:217], off
	v_lshl_add_u64 v[216:217], s[30:31], 0, v[134:135]
	s_mov_b32 m0, s25
	s_nop 0
	global_load_lds_dwordx4 v[216:217], off
	s_mov_b32 m0, s40
	s_nop 0
	global_load_lds_dwordx4 v[218:219], off
	s_waitcnt vmcnt(8)
	s_waitcnt lgkmcnt(0)
	s_setprio 1
	s_barrier

	v_mfma_f32_16x16x32_bf16 v[62:65], v[146:149], v[178:181], v[62:65]
	v_mfma_f32_16x16x32_bf16 v[58:61], v[154:157], v[178:181], v[58:61]
	v_mfma_f32_16x16x32_bf16 v[54:57], v[162:165], v[178:181], v[54:57]
	v_mfma_f32_16x16x32_bf16 v[46:49], v[170:173], v[178:181], v[46:49]
	v_mfma_f32_16x16x32_bf16 v[50:53], v[146:149], v[192:195], v[50:53]
	v_mfma_f32_16x16x32_bf16 v[42:45], v[154:157], v[192:195], v[42:45]
	v_mfma_f32_16x16x32_bf16 v[38:41], v[162:165], v[192:195], v[38:41]
	v_mfma_f32_16x16x32_bf16 v[30:33], v[170:173], v[192:195], v[30:33]
	v_mfma_f32_16x16x32_bf16 v[34:37], v[146:149], v[200:203], v[34:37]
	v_mfma_f32_16x16x32_bf16 v[26:29], v[154:157], v[200:203], v[26:29]
	v_mfma_f32_16x16x32_bf16 v[22:25], v[162:165], v[200:203], v[22:25]
	v_mfma_f32_16x16x32_bf16 v[14:17], v[170:173], v[200:203], v[14:17]
	v_mfma_f32_16x16x32_bf16 v[18:21], v[146:149], v[208:211], v[18:21]
	v_mfma_f32_16x16x32_bf16 v[10:13], v[154:157], v[208:211], v[10:13]
	v_mfma_f32_16x16x32_bf16 v[6:9], v[162:165], v[208:211], v[6:9]
	v_mfma_f32_16x16x32_bf16 v[2:5], v[170:173], v[208:211], v[2:5]


	v_mfma_f32_16x16x32_bf16 v[62:65], v[150:153], v[182:185], v[62:65]
	v_mfma_f32_16x16x32_bf16 v[58:61], v[158:161], v[182:185], v[58:61]
	v_mfma_f32_16x16x32_bf16 v[54:57], v[166:169], v[182:185], v[54:57]
	v_mfma_f32_16x16x32_bf16 v[46:49], v[174:177], v[182:185], v[46:49]
	v_mfma_f32_16x16x32_bf16 v[50:53], v[150:153], v[196:199], v[50:53]
	v_mfma_f32_16x16x32_bf16 v[42:45], v[158:161], v[196:199], v[42:45]
	v_mfma_f32_16x16x32_bf16 v[38:41], v[166:169], v[196:199], v[38:41]
	v_mfma_f32_16x16x32_bf16 v[30:33], v[174:177], v[196:199], v[30:33]
	v_mfma_f32_16x16x32_bf16 v[34:37], v[150:153], v[204:207], v[34:37]
	v_mfma_f32_16x16x32_bf16 v[26:29], v[158:161], v[204:207], v[26:29]
	v_mfma_f32_16x16x32_bf16 v[22:25], v[166:169], v[204:207], v[22:25]
	v_mfma_f32_16x16x32_bf16 v[14:17], v[174:177], v[204:207], v[14:17]
	v_mfma_f32_16x16x32_bf16 v[18:21], v[150:153], v[212:215], v[18:21]
	v_mfma_f32_16x16x32_bf16 v[10:13], v[158:161], v[212:215], v[10:13]
	v_mfma_f32_16x16x32_bf16 v[6:9], v[166:169], v[212:215], v[6:9]
	v_mfma_f32_16x16x32_bf16 v[2:5], v[174:177], v[212:215], v[2:5]
	s_barrier
	s_setprio 0
	s_add_i32 s0, 0, 0x18000
	s_add_i32 s1, 0, 0x1c000
	v_add_u32_e32 v158, s0, v144
	v_add_u32_e32 v174, s1, v144
	ds_read_b128 v[146:149], v158
	ds_read_b128 v[150:153], v158 offset:1024
	ds_read_b128 v[154:157], v158 offset:2048
	ds_read_b128 v[158:161], v158 offset:3072
	ds_read_b128 v[162:165], v174
	ds_read_b128 v[166:169], v174 offset:1024
	ds_read_b128 v[170:173], v174 offset:2048
	ds_read_b128 v[174:177], v174 offset:3072
	s_add_u32 s30, s30, 0x80000
	s_addc_u32 s31, s31, 0
	s_mov_b32 m0, s41
	v_lshl_add_u64 v[220:221], s[30:31], 0, v[134:135]
	ds_read_b128 v[178:181], v145 offset:32768
	ds_read_b128 v[182:185], v145 offset:33792
	ds_read_b128 v[192:195], v145 offset:34816
	ds_read_b128 v[196:199], v145 offset:35840
	ds_read_b128 v[200:203], v145 offset:36864
	ds_read_b128 v[204:207], v145 offset:37888
	ds_read_b128 v[208:211], v145 offset:38912
	ds_read_b128 v[212:215], v145 offset:39936
	global_load_lds_dwordx4 v[220:221], off
	v_lshl_add_u64 v[220:221], s[30:31], 0, v[132:133]
	s_mov_b32 m0, s42
	s_nop 0
	global_load_lds_dwordx4 v[220:221], off
	s_waitcnt vmcnt(8)
	s_waitcnt lgkmcnt(0)
	s_setprio 1
	s_barrier

	v_mfma_f32_16x16x32_bf16 v[126:129], v[146:149], v[178:181], v[126:129]
	v_mfma_f32_16x16x32_bf16 v[122:125], v[154:157], v[178:181], v[122:125]
	v_mfma_f32_16x16x32_bf16 v[118:121], v[162:165], v[178:181], v[118:121]
	v_mfma_f32_16x16x32_bf16 v[110:113], v[170:173], v[178:181], v[110:113]
	v_mfma_f32_16x16x32_bf16 v[114:117], v[146:149], v[192:195], v[114:117]
	v_mfma_f32_16x16x32_bf16 v[106:109], v[154:157], v[192:195], v[106:109]
	v_mfma_f32_16x16x32_bf16 v[102:105], v[162:165], v[192:195], v[102:105]
	v_mfma_f32_16x16x32_bf16 v[94:97], v[170:173], v[192:195], v[94:97]
	v_mfma_f32_16x16x32_bf16 v[98:101], v[146:149], v[200:203], v[98:101]
	v_mfma_f32_16x16x32_bf16 v[90:93], v[154:157], v[200:203], v[90:93]
	v_mfma_f32_16x16x32_bf16 v[86:89], v[162:165], v[200:203], v[86:89]
	v_mfma_f32_16x16x32_bf16 v[78:81], v[170:173], v[200:203], v[78:81]
	v_mfma_f32_16x16x32_bf16 v[82:85], v[146:149], v[208:211], v[82:85]
	v_mfma_f32_16x16x32_bf16 v[74:77], v[154:157], v[208:211], v[74:77]
	v_mfma_f32_16x16x32_bf16 v[70:73], v[162:165], v[208:211], v[70:73]
	v_mfma_f32_16x16x32_bf16 v[66:69], v[170:173], v[208:211], v[66:69]


	v_mfma_f32_16x16x32_bf16 v[126:129], v[150:153], v[182:185], v[126:129]
	v_mfma_f32_16x16x32_bf16 v[122:125], v[158:161], v[182:185], v[122:125]
	v_mfma_f32_16x16x32_bf16 v[118:121], v[166:169], v[182:185], v[118:121]
	v_mfma_f32_16x16x32_bf16 v[110:113], v[174:177], v[182:185], v[110:113]
	v_mfma_f32_16x16x32_bf16 v[114:117], v[150:153], v[196:199], v[114:117]
	v_mfma_f32_16x16x32_bf16 v[106:109], v[158:161], v[196:199], v[106:109]
	v_mfma_f32_16x16x32_bf16 v[102:105], v[166:169], v[196:199], v[102:105]
	v_mfma_f32_16x16x32_bf16 v[94:97], v[174:177], v[196:199], v[94:97]
	v_mfma_f32_16x16x32_bf16 v[98:101], v[150:153], v[204:207], v[98:101]
	v_mfma_f32_16x16x32_bf16 v[90:93], v[158:161], v[204:207], v[90:93]
	v_mfma_f32_16x16x32_bf16 v[86:89], v[166:169], v[204:207], v[86:89]
	v_mfma_f32_16x16x32_bf16 v[78:81], v[174:177], v[204:207], v[78:81]
	v_mfma_f32_16x16x32_bf16 v[82:85], v[150:153], v[212:215], v[82:85]
	v_mfma_f32_16x16x32_bf16 v[74:77], v[158:161], v[212:215], v[74:77]
	v_mfma_f32_16x16x32_bf16 v[70:73], v[166:169], v[212:215], v[70:73]
	v_mfma_f32_16x16x32_bf16 v[66:69], v[174:177], v[212:215], v[66:69]
	s_barrier
	s_setprio 0
	s_add_i32 s0, s0, s39
	v_lshl_add_u64 v[140:141], v[140:141], 0, s[84:85]
	s_mov_b32 m0, s0
	ds_read_b128 v[178:181], v145 offset:49152
	ds_read_b128 v[182:185], v145 offset:50176
	ds_read_b128 v[192:195], v145 offset:51200
	ds_read_b128 v[196:199], v145 offset:52224
	ds_read_b128 v[200:203], v145 offset:53248
	ds_read_b128 v[204:207], v145 offset:54272
	ds_read_b128 v[208:211], v145 offset:55296
	ds_read_b128 v[212:215], v145 offset:56320
	global_load_lds_dwordx4 v[140:141], off
	s_add_i32 m0, s0, 0x2000
	s_add_u32 s28, s28, 0x80080
	v_lshl_add_u64 v[140:141], v[188:189], 0, s[84:85]
	s_addc_u32 s29, s29, 0
	s_add_i32 s0, s1, s39
	global_load_lds_dwordx4 v[140:141], off
	v_lshl_add_u64 v[140:141], s[28:29], 0, v[186:187]
	s_mov_b32 m0, s0
	s_nop 0
	global_load_lds_dwordx4 v[140:141], off
	v_lshl_add_u64 v[140:141], s[28:29], 0, v[130:131]
	s_add_i32 m0, s0, 0x2000
	s_nop 0
	global_load_lds_dwordx4 v[140:141], off
	v_lshl_add_u64 v[140:141], v[216:217], 0, s[84:85]
	s_mov_b32 m0, s43
	s_nop 0
	global_load_lds_dwordx4 v[140:141], off
	v_lshl_add_u64 v[140:141], v[218:219], 0, s[84:85]
	s_mov_b32 m0, s44
	s_nop 0
	global_load_lds_dwordx4 v[140:141], off
	s_waitcnt vmcnt(8)
	s_waitcnt lgkmcnt(0)
	s_setprio 1
	s_barrier

	v_mfma_f32_16x16x32_bf16 v[62:65], v[146:149], v[178:181], v[62:65]
	v_mfma_f32_16x16x32_bf16 v[58:61], v[154:157], v[178:181], v[58:61]
	v_mfma_f32_16x16x32_bf16 v[54:57], v[162:165], v[178:181], v[54:57]
	v_mfma_f32_16x16x32_bf16 v[46:49], v[170:173], v[178:181], v[46:49]
	v_mfma_f32_16x16x32_bf16 v[50:53], v[146:149], v[192:195], v[50:53]
	v_mfma_f32_16x16x32_bf16 v[42:45], v[154:157], v[192:195], v[42:45]
	v_mfma_f32_16x16x32_bf16 v[38:41], v[162:165], v[192:195], v[38:41]
	v_mfma_f32_16x16x32_bf16 v[30:33], v[170:173], v[192:195], v[30:33]
	v_mfma_f32_16x16x32_bf16 v[34:37], v[146:149], v[200:203], v[34:37]
	v_mfma_f32_16x16x32_bf16 v[26:29], v[154:157], v[200:203], v[26:29]
	v_mfma_f32_16x16x32_bf16 v[22:25], v[162:165], v[200:203], v[22:25]
	v_mfma_f32_16x16x32_bf16 v[14:17], v[170:173], v[200:203], v[14:17]
	v_mfma_f32_16x16x32_bf16 v[18:21], v[146:149], v[208:211], v[18:21]
	v_mfma_f32_16x16x32_bf16 v[10:13], v[154:157], v[208:211], v[10:13]
	v_mfma_f32_16x16x32_bf16 v[6:9], v[162:165], v[208:211], v[6:9]
	v_mfma_f32_16x16x32_bf16 v[2:5], v[170:173], v[208:211], v[2:5]


	v_mfma_f32_16x16x32_bf16 v[62:65], v[150:153], v[182:185], v[62:65]
	v_mfma_f32_16x16x32_bf16 v[58:61], v[158:161], v[182:185], v[58:61]
	v_mfma_f32_16x16x32_bf16 v[54:57], v[166:169], v[182:185], v[54:57]
	v_mfma_f32_16x16x32_bf16 v[46:49], v[174:177], v[182:185], v[46:49]
	v_mfma_f32_16x16x32_bf16 v[50:53], v[150:153], v[196:199], v[50:53]
	v_mfma_f32_16x16x32_bf16 v[42:45], v[158:161], v[196:199], v[42:45]
	v_mfma_f32_16x16x32_bf16 v[38:41], v[166:169], v[196:199], v[38:41]
	v_mfma_f32_16x16x32_bf16 v[30:33], v[174:177], v[196:199], v[30:33]
	v_mfma_f32_16x16x32_bf16 v[34:37], v[150:153], v[204:207], v[34:37]
	v_mfma_f32_16x16x32_bf16 v[26:29], v[158:161], v[204:207], v[26:29]
	v_mfma_f32_16x16x32_bf16 v[22:25], v[166:169], v[204:207], v[22:25]
	v_mfma_f32_16x16x32_bf16 v[14:17], v[174:177], v[204:207], v[14:17]
	v_mfma_f32_16x16x32_bf16 v[18:21], v[150:153], v[212:215], v[18:21]
	v_mfma_f32_16x16x32_bf16 v[10:13], v[158:161], v[212:215], v[10:13]
	v_mfma_f32_16x16x32_bf16 v[6:9], v[166:169], v[212:215], v[6:9]
	v_mfma_f32_16x16x32_bf16 v[2:5], v[174:177], v[212:215], v[2:5]
	s_barrier
	s_setprio 0
	s_add_i32 s55, s55, 2
	s_add_u32 s26, s26, 0x100
	s_addc_u32 s27, s27, 0
	s_add_u32 s53, s53, 0x100
	s_addc_u32 s54, s54, 0
	s_cmp_gt_u32 s55, 29
	s_cbranch_scc0 .LBB0_443
	s_and_b64 vcc, exec, s[14:15]
	s_cbranch_vccz .LBB0_446
	s_barrier

.LBB0_1126:
	s_add_u32 s0, s28, 0xfff80080
	s_addc_u32 s1, s29, -1
	s_add_i32 s54, 0, 0x10000
	s_cmp_eq_u32 s53, 28
	s_cselect_b32 s35, s19, s1
	s_cselect_b32 s34, s25, s0
	s_cselect_b32 s31, s17, s52
	s_cselect_b32 s30, s27, s51
	s_add_i32 s55, 0, 0x14000
	v_add_u32_e32 v126, s54, v237
	v_add_u32_e32 v158, s55, v237
	ds_read_b128 v[90:93], v126
	ds_read_b128 v[102:105], v126 offset:1024
	ds_read_b128 v[114:117], v126 offset:2048
	ds_read_b128 v[126:129], v126 offset:3072
	ds_read_b128 v[138:141], v158
	ds_read_b128 v[142:145], v158 offset:1024
	ds_read_b128 v[154:157], v158 offset:2048
	ds_read_b128 v[158:161], v158 offset:3072
	v_lshl_add_u64 v[188:189], s[28:29], 0, v[198:199]
	s_add_i32 m0, s40, 0xc000
	ds_read_b128 v[162:165], v238
	ds_read_b128 v[166:169], v238 offset:1024
	ds_read_b128 v[170:173], v238 offset:2048
	ds_read_b128 v[174:177], v238 offset:3072
	ds_read_b128 v[178:181], v238 offset:4096
	ds_read_b128 v[182:185], v238 offset:5120
	ds_read_b128 v[202:205], v238 offset:6144
	ds_read_b128 v[206:209], v238 offset:7168
	global_load_lds_dwordx4 v[188:189], off
	v_lshl_add_u64 v[188:189], s[28:29], 0, v[200:201]
	s_add_i32 m0, s40, 0xe000
	s_nop 0
	global_load_lds_dwordx4 v[188:189], off
	s_waitcnt vmcnt(8)
	s_waitcnt lgkmcnt(0)
	s_setprio 1
	s_barrier

	v_mfma_f32_16x16x32_bf16 v[150:153], v[90:93], v[162:165], v[150:153]
	v_mfma_f32_16x16x32_bf16 v[146:149], v[114:117], v[162:165], v[146:149]
	v_mfma_f32_16x16x32_bf16 v[134:137], v[138:141], v[162:165], v[134:137]
	v_mfma_f32_16x16x32_bf16 v[130:133], v[154:157], v[162:165], v[130:133]
	v_mfma_f32_16x16x32_bf16 v[122:125], v[90:93], v[170:173], v[122:125]
	v_mfma_f32_16x16x32_bf16 v[118:121], v[114:117], v[170:173], v[118:121]
	v_mfma_f32_16x16x32_bf16 v[110:113], v[138:141], v[170:173], v[110:113]
	v_mfma_f32_16x16x32_bf16 v[106:109], v[154:157], v[170:173], v[106:109]
	v_mfma_f32_16x16x32_bf16 v[98:101], v[90:93], v[178:181], v[98:101]
	v_mfma_f32_16x16x32_bf16 v[94:97], v[114:117], v[178:181], v[94:97]
	v_mfma_f32_16x16x32_bf16 v[86:89], v[138:141], v[178:181], v[86:89]
	v_mfma_f32_16x16x32_bf16 v[82:85], v[154:157], v[178:181], v[82:85]
	v_mfma_f32_16x16x32_bf16 v[78:81], v[90:93], v[202:205], v[78:81]
	v_mfma_f32_16x16x32_bf16 v[74:77], v[114:117], v[202:205], v[74:77]
	v_mfma_f32_16x16x32_bf16 v[70:73], v[138:141], v[202:205], v[70:73]
	v_mfma_f32_16x16x32_bf16 v[66:69], v[154:157], v[202:205], v[66:69]


	v_mfma_f32_16x16x32_bf16 v[150:153], v[102:105], v[166:169], v[150:153]
	v_mfma_f32_16x16x32_bf16 v[146:149], v[126:129], v[166:169], v[146:149]
	v_mfma_f32_16x16x32_bf16 v[134:137], v[142:145], v[166:169], v[134:137]
	v_mfma_f32_16x16x32_bf16 v[130:133], v[158:161], v[166:169], v[130:133]
	v_mfma_f32_16x16x32_bf16 v[122:125], v[102:105], v[174:177], v[122:125]
	v_mfma_f32_16x16x32_bf16 v[118:121], v[126:129], v[174:177], v[118:121]
	v_mfma_f32_16x16x32_bf16 v[110:113], v[142:145], v[174:177], v[110:113]
	v_mfma_f32_16x16x32_bf16 v[106:109], v[158:161], v[174:177], v[106:109]
	v_mfma_f32_16x16x32_bf16 v[98:101], v[102:105], v[182:185], v[98:101]
	v_mfma_f32_16x16x32_bf16 v[94:97], v[126:129], v[182:185], v[94:97]
	v_mfma_f32_16x16x32_bf16 v[86:89], v[142:145], v[182:185], v[86:89]
	v_mfma_f32_16x16x32_bf16 v[82:85], v[158:161], v[182:185], v[82:85]
	v_mfma_f32_16x16x32_bf16 v[78:81], v[102:105], v[206:209], v[78:81]
	v_mfma_f32_16x16x32_bf16 v[74:77], v[126:129], v[206:209], v[74:77]
	v_mfma_f32_16x16x32_bf16 v[70:73], v[142:145], v[206:209], v[70:73]
	v_mfma_f32_16x16x32_bf16 v[66:69], v[158:161], v[206:209], v[66:69]
	s_barrier
	s_setprio 0
	s_add_i32 s0, s54, s39
	v_lshl_add_u64 v[188:189], s[30:31], 0, v[186:187]
	s_mov_b32 m0, s0
	ds_read_b128 v[162:165], v238 offset:16384
	ds_read_b128 v[166:169], v238 offset:17408
	ds_read_b128 v[170:173], v238 offset:18432
	ds_read_b128 v[174:177], v238 offset:19456
	ds_read_b128 v[178:181], v238 offset:20480
	ds_read_b128 v[182:185], v238 offset:21504
	ds_read_b128 v[202:205], v238 offset:22528
	ds_read_b128 v[206:209], v238 offset:23552
	global_load_lds_dwordx4 v[188:189], off
	s_add_i32 m0, s0, 0x2000
	s_add_u32 s0, s30, 0x80000
	v_lshl_add_u64 v[210:211], s[30:31], 0, v[196:197]
	s_addc_u32 s1, s31, 0
	s_add_i32 s54, s55, s39
	global_load_lds_dwordx4 v[210:211], off
	v_lshl_add_u64 v[212:213], s[0:1], 0, v[186:187]
	s_mov_b32 m0, s54
	v_lshl_add_u64 v[214:215], s[34:35], 0, v[194:195]
	global_load_lds_dwordx4 v[212:213], off
	v_lshl_add_u64 v[212:213], s[0:1], 0, v[196:197]
	s_add_i32 m0, s54, 0x2000
	s_nop 0
	global_load_lds_dwordx4 v[212:213], off
	v_lshl_add_u64 v[212:213], s[34:35], 0, v[192:193]
	s_mov_b32 m0, s40
	s_nop 0
	global_load_lds_dwordx4 v[212:213], off
	s_mov_b32 m0, s41
	s_nop 0
	global_load_lds_dwordx4 v[214:215], off
	s_waitcnt vmcnt(8)
	s_waitcnt lgkmcnt(0)
	s_setprio 1
	s_barrier

	v_mfma_f32_16x16x32_bf16 v[62:65], v[90:93], v[162:165], v[62:65]
	v_mfma_f32_16x16x32_bf16 v[58:61], v[114:117], v[162:165], v[58:61]
	v_mfma_f32_16x16x32_bf16 v[54:57], v[138:141], v[162:165], v[54:57]
	v_mfma_f32_16x16x32_bf16 v[50:53], v[154:157], v[162:165], v[50:53]
	v_mfma_f32_16x16x32_bf16 v[46:49], v[90:93], v[170:173], v[46:49]
	v_mfma_f32_16x16x32_bf16 v[42:45], v[114:117], v[170:173], v[42:45]
	v_mfma_f32_16x16x32_bf16 v[38:41], v[138:141], v[170:173], v[38:41]
	v_mfma_f32_16x16x32_bf16 v[34:37], v[154:157], v[170:173], v[34:37]
	v_mfma_f32_16x16x32_bf16 v[30:33], v[90:93], v[178:181], v[30:33]
	v_mfma_f32_16x16x32_bf16 v[26:29], v[114:117], v[178:181], v[26:29]
	v_mfma_f32_16x16x32_bf16 v[22:25], v[138:141], v[178:181], v[22:25]
	v_mfma_f32_16x16x32_bf16 v[18:21], v[154:157], v[178:181], v[18:21]
	v_mfma_f32_16x16x32_bf16 v[14:17], v[90:93], v[202:205], v[14:17]
	v_mfma_f32_16x16x32_bf16 v[10:13], v[114:117], v[202:205], v[10:13]
	v_mfma_f32_16x16x32_bf16 v[6:9], v[138:141], v[202:205], v[6:9]
	v_mfma_f32_16x16x32_bf16 v[2:5], v[154:157], v[202:205], v[2:5]


	v_mfma_f32_16x16x32_bf16 v[62:65], v[102:105], v[166:169], v[62:65]
	v_mfma_f32_16x16x32_bf16 v[58:61], v[126:129], v[166:169], v[58:61]
	v_mfma_f32_16x16x32_bf16 v[54:57], v[142:145], v[166:169], v[54:57]
	v_mfma_f32_16x16x32_bf16 v[50:53], v[158:161], v[166:169], v[50:53]
	v_mfma_f32_16x16x32_bf16 v[46:49], v[102:105], v[174:177], v[46:49]
	v_mfma_f32_16x16x32_bf16 v[42:45], v[126:129], v[174:177], v[42:45]
	v_mfma_f32_16x16x32_bf16 v[38:41], v[142:145], v[174:177], v[38:41]
	v_mfma_f32_16x16x32_bf16 v[34:37], v[158:161], v[174:177], v[34:37]
	v_mfma_f32_16x16x32_bf16 v[30:33], v[102:105], v[182:185], v[30:33]
	v_mfma_f32_16x16x32_bf16 v[26:29], v[126:129], v[182:185], v[26:29]
	v_mfma_f32_16x16x32_bf16 v[22:25], v[142:145], v[182:185], v[22:25]
	v_mfma_f32_16x16x32_bf16 v[18:21], v[158:161], v[182:185], v[18:21]
	v_mfma_f32_16x16x32_bf16 v[14:17], v[102:105], v[206:209], v[14:17]
	v_mfma_f32_16x16x32_bf16 v[10:13], v[126:129], v[206:209], v[10:13]
	v_mfma_f32_16x16x32_bf16 v[6:9], v[142:145], v[206:209], v[6:9]
	v_mfma_f32_16x16x32_bf16 v[2:5], v[158:161], v[206:209], v[2:5]
	s_barrier
	s_setprio 0
	s_add_i32 s54, 0, 0x18000
	s_add_i32 s55, 0, 0x1c000
	v_add_u32_e32 v126, s54, v237
	v_add_u32_e32 v158, s55, v237
	ds_read_b128 v[90:93], v126
	ds_read_b128 v[102:105], v126 offset:1024
	ds_read_b128 v[114:117], v126 offset:2048
	ds_read_b128 v[126:129], v126 offset:3072
	ds_read_b128 v[138:141], v158
	ds_read_b128 v[142:145], v158 offset:1024
	ds_read_b128 v[154:157], v158 offset:2048
	ds_read_b128 v[158:161], v158 offset:3072
	s_add_u32 s0, s34, 0x80000
	s_addc_u32 s1, s35, 0
	s_mov_b32 m0, s42
	v_lshl_add_u64 v[216:217], s[0:1], 0, v[192:193]
	ds_read_b128 v[162:165], v238 offset:32768
	ds_read_b128 v[166:169], v238 offset:33792
	ds_read_b128 v[170:173], v238 offset:34816
	ds_read_b128 v[174:177], v238 offset:35840
	ds_read_b128 v[178:181], v238 offset:36864
	ds_read_b128 v[182:185], v238 offset:37888
	ds_read_b128 v[202:205], v238 offset:38912
	ds_read_b128 v[206:209], v238 offset:39936
	global_load_lds_dwordx4 v[216:217], off
	v_lshl_add_u64 v[216:217], s[0:1], 0, v[194:195]
	s_mov_b32 m0, s43
	s_nop 0
	global_load_lds_dwordx4 v[216:217], off
	s_waitcnt vmcnt(8)
	s_waitcnt lgkmcnt(0)
	s_setprio 1
	s_barrier

	v_mfma_f32_16x16x32_bf16 v[150:153], v[90:93], v[162:165], v[150:153]
	v_mfma_f32_16x16x32_bf16 v[146:149], v[114:117], v[162:165], v[146:149]
	v_mfma_f32_16x16x32_bf16 v[134:137], v[138:141], v[162:165], v[134:137]
	v_mfma_f32_16x16x32_bf16 v[130:133], v[154:157], v[162:165], v[130:133]
	v_mfma_f32_16x16x32_bf16 v[122:125], v[90:93], v[170:173], v[122:125]
	v_mfma_f32_16x16x32_bf16 v[118:121], v[114:117], v[170:173], v[118:121]
	v_mfma_f32_16x16x32_bf16 v[110:113], v[138:141], v[170:173], v[110:113]
	v_mfma_f32_16x16x32_bf16 v[106:109], v[154:157], v[170:173], v[106:109]
	v_mfma_f32_16x16x32_bf16 v[98:101], v[90:93], v[178:181], v[98:101]
	v_mfma_f32_16x16x32_bf16 v[94:97], v[114:117], v[178:181], v[94:97]
	v_mfma_f32_16x16x32_bf16 v[86:89], v[138:141], v[178:181], v[86:89]
	v_mfma_f32_16x16x32_bf16 v[82:85], v[154:157], v[178:181], v[82:85]
	v_mfma_f32_16x16x32_bf16 v[78:81], v[90:93], v[202:205], v[78:81]
	v_mfma_f32_16x16x32_bf16 v[74:77], v[114:117], v[202:205], v[74:77]
	v_mfma_f32_16x16x32_bf16 v[70:73], v[138:141], v[202:205], v[70:73]
	v_mfma_f32_16x16x32_bf16 v[66:69], v[154:157], v[202:205], v[66:69]


	v_mfma_f32_16x16x32_bf16 v[150:153], v[102:105], v[166:169], v[150:153]
	v_mfma_f32_16x16x32_bf16 v[146:149], v[126:129], v[166:169], v[146:149]
	v_mfma_f32_16x16x32_bf16 v[134:137], v[142:145], v[166:169], v[134:137]
	v_mfma_f32_16x16x32_bf16 v[130:133], v[158:161], v[166:169], v[130:133]
	v_mfma_f32_16x16x32_bf16 v[122:125], v[102:105], v[174:177], v[122:125]
	v_mfma_f32_16x16x32_bf16 v[118:121], v[126:129], v[174:177], v[118:121]
	v_mfma_f32_16x16x32_bf16 v[110:113], v[142:145], v[174:177], v[110:113]
	v_mfma_f32_16x16x32_bf16 v[106:109], v[158:161], v[174:177], v[106:109]
	v_mfma_f32_16x16x32_bf16 v[98:101], v[102:105], v[182:185], v[98:101]
	v_mfma_f32_16x16x32_bf16 v[94:97], v[126:129], v[182:185], v[94:97]
	v_mfma_f32_16x16x32_bf16 v[86:89], v[142:145], v[182:185], v[86:89]
	v_mfma_f32_16x16x32_bf16 v[82:85], v[158:161], v[182:185], v[82:85]
	v_mfma_f32_16x16x32_bf16 v[78:81], v[102:105], v[206:209], v[78:81]
	v_mfma_f32_16x16x32_bf16 v[74:77], v[126:129], v[206:209], v[74:77]
	v_mfma_f32_16x16x32_bf16 v[70:73], v[142:145], v[206:209], v[70:73]
	v_mfma_f32_16x16x32_bf16 v[66:69], v[158:161], v[206:209], v[66:69]
	s_barrier
	s_setprio 0
	s_add_i32 s0, s54, s39
	v_lshl_add_u64 v[188:189], v[188:189], 0, s[84:85]
	s_mov_b32 m0, s0
	ds_read_b128 v[162:165], v238 offset:49152
	ds_read_b128 v[166:169], v238 offset:50176
	ds_read_b128 v[170:173], v238 offset:51200
	ds_read_b128 v[174:177], v238 offset:52224
	ds_read_b128 v[178:181], v238 offset:53248
	ds_read_b128 v[182:185], v238 offset:54272
	ds_read_b128 v[202:205], v238 offset:55296
	ds_read_b128 v[206:209], v238 offset:56320
	global_load_lds_dwordx4 v[188:189], off
	s_add_i32 m0, s0, 0x2000
	s_add_u32 s0, s30, 0x80080
	v_lshl_add_u64 v[188:189], v[210:211], 0, s[84:85]
	s_addc_u32 s1, s31, 0
	s_add_i32 s30, s55, s39
	global_load_lds_dwordx4 v[188:189], off
	v_lshl_add_u64 v[188:189], s[0:1], 0, v[186:187]
	s_mov_b32 m0, s30
	s_nop 0
	global_load_lds_dwordx4 v[188:189], off
	v_lshl_add_u64 v[188:189], s[0:1], 0, v[196:197]
	s_add_i32 m0, s30, 0x2000
	s_nop 0
	global_load_lds_dwordx4 v[188:189], off
	v_lshl_add_u64 v[188:189], v[212:213], 0, s[84:85]
	s_mov_b32 m0, s47
	s_nop 0
	global_load_lds_dwordx4 v[188:189], off
	v_lshl_add_u64 v[188:189], v[214:215], 0, s[84:85]
	s_mov_b32 m0, s48
	s_nop 0
	global_load_lds_dwordx4 v[188:189], off
	s_waitcnt vmcnt(8)
	s_waitcnt lgkmcnt(0)
	s_setprio 1
	s_barrier

	v_mfma_f32_16x16x32_bf16 v[62:65], v[90:93], v[162:165], v[62:65]
	v_mfma_f32_16x16x32_bf16 v[58:61], v[114:117], v[162:165], v[58:61]
	v_mfma_f32_16x16x32_bf16 v[54:57], v[138:141], v[162:165], v[54:57]
	v_mfma_f32_16x16x32_bf16 v[50:53], v[154:157], v[162:165], v[50:53]
	v_mfma_f32_16x16x32_bf16 v[46:49], v[90:93], v[170:173], v[46:49]
	v_mfma_f32_16x16x32_bf16 v[42:45], v[114:117], v[170:173], v[42:45]
	v_mfma_f32_16x16x32_bf16 v[38:41], v[138:141], v[170:173], v[38:41]
	v_mfma_f32_16x16x32_bf16 v[34:37], v[154:157], v[170:173], v[34:37]
	v_mfma_f32_16x16x32_bf16 v[30:33], v[90:93], v[178:181], v[30:33]
	v_mfma_f32_16x16x32_bf16 v[26:29], v[114:117], v[178:181], v[26:29]
	v_mfma_f32_16x16x32_bf16 v[22:25], v[138:141], v[178:181], v[22:25]
	v_mfma_f32_16x16x32_bf16 v[18:21], v[154:157], v[178:181], v[18:21]
	v_mfma_f32_16x16x32_bf16 v[14:17], v[90:93], v[202:205], v[14:17]
	v_mfma_f32_16x16x32_bf16 v[10:13], v[114:117], v[202:205], v[10:13]
	v_mfma_f32_16x16x32_bf16 v[6:9], v[138:141], v[202:205], v[6:9]
	v_mfma_f32_16x16x32_bf16 v[2:5], v[154:157], v[202:205], v[2:5]


	v_mfma_f32_16x16x32_bf16 v[62:65], v[102:105], v[166:169], v[62:65]
	v_mfma_f32_16x16x32_bf16 v[58:61], v[126:129], v[166:169], v[58:61]
	v_mfma_f32_16x16x32_bf16 v[54:57], v[142:145], v[166:169], v[54:57]
	v_mfma_f32_16x16x32_bf16 v[50:53], v[158:161], v[166:169], v[50:53]
	v_mfma_f32_16x16x32_bf16 v[46:49], v[102:105], v[174:177], v[46:49]
	v_mfma_f32_16x16x32_bf16 v[42:45], v[126:129], v[174:177], v[42:45]
	v_mfma_f32_16x16x32_bf16 v[38:41], v[142:145], v[174:177], v[38:41]
	v_mfma_f32_16x16x32_bf16 v[34:37], v[158:161], v[174:177], v[34:37]
	v_mfma_f32_16x16x32_bf16 v[30:33], v[102:105], v[182:185], v[30:33]
	v_mfma_f32_16x16x32_bf16 v[26:29], v[126:129], v[182:185], v[26:29]
	v_mfma_f32_16x16x32_bf16 v[22:25], v[142:145], v[182:185], v[22:25]
	v_mfma_f32_16x16x32_bf16 v[18:21], v[158:161], v[182:185], v[18:21]
	v_mfma_f32_16x16x32_bf16 v[14:17], v[102:105], v[206:209], v[14:17]
	v_mfma_f32_16x16x32_bf16 v[10:13], v[126:129], v[206:209], v[10:13]
	v_mfma_f32_16x16x32_bf16 v[6:9], v[142:145], v[206:209], v[6:9]
	v_mfma_f32_16x16x32_bf16 v[2:5], v[158:161], v[206:209], v[2:5]
	s_barrier
	s_setprio 0
	s_add_i32 s53, s53, 2
	s_add_u32 s28, s28, 0x100
	s_addc_u32 s29, s29, 0
	s_add_u32 s51, s51, 0x100
	s_addc_u32 s52, s52, 0
	s_cmp_gt_u32 s53, 29
	s_cbranch_scc0 .LBB0_1126
	s_and_b64 vcc, exec, s[14:15]
	s_cbranch_vccz .LBB0_1129
	s_barrier
